# GEMM unit loop: dropped the full vmcnt(0) drain at the top of each 256x256 unit; epilogue stores and prefetched tiles stay in flight behind the counted waits
# speedup vs baseline: 1.0292x; 1.0292x over previous
;     __host__ __device__ bool next(int i, Unit& u) const {
;         const long L = (long)i * G + c; if (L >= nwg) return false;
;         int wgid = (int)L; { const int q = nwg / NXCD, r = nwg % NXCD, xcd = wgid % NXCD, off = wgid / NXCD; wgid = (xcd < r ? xcd * (q + 1) : r * (q + 1) + (xcd - r) * q) + off; }
;         const int nig = WGM * nN, gid = wgid / nig, fm = gid * WGM, gsz = (nM - fm) < WGM ? (nM - fm) : WGM;
;         u.pm = fm + ((wgid % nig) % gsz); u.pn = (wgid % nig) / gsz; return true;
;     }
; template <class Epi, class Sched, bool ALIGN_EPI = false, bool SP2 = false>
; __device__ __forceinline__ void gemm_phase(PG8_LAS unsigned char* lds, const Gemm g, const Sched& S, const Epi& E, const int tid_in) {
;     ...
;         const bool has_next = S.next(ui + 1, nxt);
;         const char* nA = has_next ? (const char*)g.A + (size_t)nxt.pm * tstep : cA; const char* nB = has_next ? (const char*)g.Bt + (size_t)nxt.pn * tstep : cB;
.LBB0_108:
	s_add_i32 s76, s73, 1
	v_readlane_b32 s7, v255, 10
	s_mul_hi_i32 s6, s76, s7
	s_mul_i32 s7, s76, s7
	s_add_u32 s8, s7, s17
	s_addc_u32 s9, s6, s71
	v_mov_b64_e32 v[130:131], s[34:35]
	v_cmp_ge_i64_e64 s[6:7], s[8:9], v[130:131]
	v_cmp_lt_i64_e64 s[10:11], s[8:9], v[130:131]
	s_and_b64 vcc, exec, s[6:7]
	s_cbranch_vccnz .LBB0_110
	s_ashr_i32 s9, s8, 31
	s_lshr_b32 s9, s9, 29
	s_add_i32 s9, s8, s9
	s_ashr_i32 s42, s9, 3
	s_and_b32 s9, s9, -8
	s_sub_i32 s8, s8, s9
	s_lshr_b32 s9, s8, 31
	s_or_b32 s9, s69, s9
	s_mul_i32 s8, s9, s8
	s_add_i32 s8, s8, s42
	s_abs_i32 s42, s8
	s_mul_hi_u32 s43, s42, s72
	s_mul_i32 s48, s43, s69
	s_sub_i32 s42, s42, s48
	s_ashr_i32 s9, s8, 31
	s_add_i32 s48, s43, 1
	s_sub_i32 s49, s42, s69
	s_cmp_ge_u32 s42, s69
	s_cselect_b32 s43, s48, s43
	s_cselect_b32 s42, s49, s42
	s_add_i32 s48, s43, 1
	s_cmp_ge_u32 s42, s69
	s_cselect_b32 s42, s48, s43
	s_xor_b32 s42, s42, s9
	s_sub_i32 s9, s42, s9
	s_lshl_b32 s42, s9, 3
	s_sub_i32 s43, 64, s42
	s_min_i32 s43, s43, 8
	s_abs_i32 s48, s43
	v_cvt_f32_u32_e32 v0, s48
	s_sub_i32 s52, 0, s48
	s_mul_i32 s9, s9, s69
	s_sub_i32 s8, s8, s9
	v_rcp_iflag_f32_e32 v0, v0
	s_abs_i32 s49, s8
	s_xor_b32 s9, s8, s43
	s_ashr_i32 s9, s9, 31
	v_mul_f32_e32 v0, 0x4f7ffffe, v0
	v_cvt_u32_f32_e32 v0, v0
	s_nop 0
	v_readfirstlane_b32 s53, v0
	s_mul_i32 s52, s52, s53
	s_mul_hi_u32 s52, s53, s52
	s_add_i32 s53, s53, s52
	s_mul_hi_u32 s52, s49, s53
	s_mul_i32 s53, s52, s48
	s_sub_i32 s49, s49, s53
	s_add_i32 s53, s52, 1
	s_sub_i32 s74, s49, s48
	s_cmp_ge_u32 s49, s48
	s_cselect_b32 s52, s53, s52
	s_cselect_b32 s49, s74, s49
	s_add_i32 s53, s52, 1
	s_cmp_ge_u32 s49, s48
	s_cselect_b32 s48, s53, s52
	s_xor_b32 s48, s48, s9
	s_sub_i32 s74, s48, s9
	s_mul_i32 s9, s74, s43
	s_sub_i32 s8, s8, s9
	s_add_i32 s75, s8, s42

; #define LAS __attribute__((address_space(3)))
; __global__ void __launch_bounds__(NTHREADS, 2) fwd_megakernel(Params p_) {
;     ...
;         const bool even = (L & 1) == 0; const int li = L >> 1;
;         if (s == 3) {
;             unsigned* qctr = (unsigned*)(ws + WS_CTL + CTL_Q) + 64 * L;
;             volatile LAS unsigned* qslot = (volatile LAS unsigned*)(lds + LDS_MISC + 16);
;             const int total = even ? 1024 : 640;
.LBB0_317:
	s_and_b64 vcc, exec, s[0:1]
	s_cbranch_vccz .LBB0_494
	s_lshl_b32 s2, s13, 6
	s_ashr_i32 s3, s2, 31
	s_ashr_i32 s0, s13, 1
	s_lshl_b64 s[2:3], s[2:3], 2
	s_add_u32 s1, s96, s2
	s_addc_u32 s2, s97, s3
	s_add_u32 s4, s1, 0x1590c000
	s_addc_u32 s5, s2, 0
	s_and_b64 s[2:3], s[28:29], exec
	s_movk_i32 s1, 0x280
	v_writelane_b32 v255, s4, 18
	s_cselect_b32 s13, 0x400, s1
	s_lshl_b32 s2, s0, 9
	v_writelane_b32 v255, s5, 19
	s_ashr_i32 s3, s2, 31
	v_writelane_b32 v255, s2, 20
	s_ashr_i32 s1, s0, 31
	v_cmp_eq_u32_e64 s[18:19], 0, v236
	v_writelane_b32 v255, s3, 21
	s_lshl_b64 s[2:3], s[0:1], 18
	v_writelane_b32 v255, s2, 22
	s_mul_hi_i32 s1, s0, 0xf800
	s_mul_i32 s0, s0, 0xf800
	v_writelane_b32 v255, s3, 23
	v_writelane_b32 v255, s1, 24
	v_writelane_b32 v255, s0, 25
	s_add_u32 s0, s96, 0xc100400
	v_writelane_b32 v255, s0, 26
	s_addc_u32 s0, s97, 0
	v_writelane_b32 v255, s0, 27
	s_add_u32 s0, s96, 0xc1f0400
	s_addc_u32 s1, s97, 0
	v_writelane_b32 v255, s0, 28
	s_nop 1
	v_writelane_b32 v255, s1, 29
	v_writelane_b32 v255, s13, 30
	v_writelane_b32 v255, s18, 32
	s_nop 1
	v_writelane_b32 v255, s19, 33
	v_writelane_b32 v255, s84, 34
	s_nop 1
	v_writelane_b32 v255, s85, 35
	s_branch .LBB0_322

; __device__ __forceinline__ void moba_unit(LAS unsigned char* lds, const bf16* PROJ, bf16* MIX, int b, int h, int j, int tid) {
;     const int lane = tid & 63, wid = __builtin_amdgcn_readfirstlane(tid >> 6), r32 = lane & 31, hi = lane >> 5;
;     const size_t rowbase = (size_t)b * SEQ; const int q0 = 256 * j;
;     const bf16* Kg = PROJ + rowbase * NPROJ + 512 + h * 64; const bf16* Vg = PROJ + rowbase * NPROJ + 1024 + h * 64;
;     const bf16* Qp = PROJ + (rowbase + q0 + 32 * wid + r32) * NPROJ + h * 64;
;     bf16x8 qr[4];
; #pragma unroll
;     for (int d0 = 0; d0 < 4; ++d0) qr[d0] = *(const bf16x8*)(Qp + 16 * d0 + 8 * hi);
;     u32x4 kr, vr, kr1, vr1; tile_load(Kg, Vg, q0, tid, kr, vr); tile_load(Kg, Vg, q0 + 64, tid, kr1, vr1);
;     LAS float* km = (LAS float*)(lds + OFF_KM); LAS float* part = (LAS float*)(lds + OFF_PART);
;     { const int ch = tid & 7, rr = tid >> 3;
;       for (int n = 0; n < j; ++n) { float a[8];
; #pragma unroll
;         for (int e = 0; e < 8; ++e) a[e] = 0.f;
; #pragma unroll
;         for (int i = 0; i < 4; ++i) { const u32x4 v = *(const u32x4*)(Kg + (size_t)(256 * n + rr + 64 * i) * NPROJ + ch * 8);
;             a[0] += bflo(v.x); a[1] += bfhi(v.x); a[2] += bflo(v.y); a[3] += bfhi(v.y); a[4] += bflo(v.z); a[5] += bfhi(v.z); a[6] += bflo(v.w); a[7] += bfhi(v.w); }
; #pragma unroll
;         for (int e = 0; e < 8; ++e) { a[e] += shx(a[e], 8, lane); a[e] += shx(a[e], 16, lane); a[e] += shx(a[e], 32, lane); }
;         if (lane < 8) {
; #pragma unroll
;             for (int e = 0; e < 8; ++e) part[(n * 8 + wid) * 64 + lane * 8 + e] = a[e]; } }
;       __syncthreads();
;       if (tid < 64) for (int n = 0; n < j; ++n) { float s = 0.f;
; __global__ void __launch_bounds__(NTHREADS, 2) fwd_megakernel(Params p_) {
;     ...
;             for (;;) {
;                 if (tid == 0) *qslot = __hip_atomic_fetch_add(qctr, 1u, __ATOMIC_RELAXED, __HIP_MEMORY_SCOPE_AGENT);
;                 __syncthreads();
;                 const int idx = __builtin_amdgcn_readfirstlane((int)*qslot);
;                 __syncthreads();
;                 if (idx >= total) break;
;                 int tq_; asm volatile("v_mov_b32 %0, %1" : "=v"(tq_) : "v"(tid));
;                 const int tq = tq_;
;                 if (even) {
;                     if (idx < 512) { const int j = 7 - (idx >> 6), bh = idx & 63; mx::moba_unit(lds, PROJ, MIX, bh >> 3, bh & 7, j, tq); }
.LBB0_322:
	s_and_saveexec_b64 s[0:1], s[18:19]
	s_cbranch_execz .LBB0_326
	s_mov_b64 s[8:9], exec
	v_mbcnt_lo_u32_b32 v0, s8, 0
	v_mbcnt_hi_u32_b32 v0, s9, v0
	v_cmp_eq_u32_e32 vcc, 0, v0
	s_and_saveexec_b64 s[2:3], vcc
	s_cbranch_execz .LBB0_325
	s_bcnt1_i32_b64 s4, s[8:9]
	v_mov_b32_e32 v2, s4
	v_readlane_b32 s4, v255, 18
	v_readlane_b32 s5, v255, 19
	s_nop 4
	global_atomic_add v2, v1, v2, s[4:5] sc0
.LBB0_325:
	s_or_b64 exec, exec, s[2:3]
	s_waitcnt vmcnt(0)
	v_readfirstlane_b32 s2, v2
	v_mov_b32_e32 v2, s76
	s_nop 0
	v_add_u32_e32 v0, s2, v0
	ds_write_b32 v2, v0
.LBB0_326:
	s_or_b64 exec, exec, s[0:1]
	v_mov_b32_e32 v0, s76
	s_waitcnt vmcnt(0) lgkmcnt(0)
	s_barrier
	ds_read_b32 v0, v0
	s_mov_b64 s[0:1], -1
	s_waitcnt lgkmcnt(0)
	s_barrier
	v_readfirstlane_b32 s24, v0
	s_cmp_ge_i32 s24, s13
	s_cbranch_scc1 .LBB0_321
	s_and_b64 vcc, exec, s[92:93]
	v_mov_b32 v200, v236
	s_cbranch_vccz .LBB0_367
	s_cmpk_gt_i32 s24, 0x7f
	s_cbranch_scc0 .LBB0_357
	s_add_i32 s0, s24, 0xffffff80
	s_lshr_b32 s4, s0, 6
	v_readfirstlane_b32 s0, v200
	s_ashr_i32 s5, s0, 6
	s_lshl_b32 s0, s24, 8
	s_sub_i32 s6, 7, s4
	s_and_b32 s0, s0, 0x3800
	s_lshl_b32 s7, s6, 8
	s_mul_i32 s1, s0, 0x1400
	s_add_u32 s2, s84, s1
	s_addc_u32 s3, s85, 0
	s_lshl_b32 s1, s24, 6
	s_and_b32 s10, s1, 0x1c0
	s_ashr_i32 s1, s7, 31
	s_add_u32 s0, s7, s0
	v_and_b32_e32 v5, 31, v200
	s_addc_u32 s1, s1, 0
	s_lshl_b32 s8, s5, 5
	s_ashr_i32 s9, s8, 31
	v_or_b32_e32 v2, s0, v5
	v_mov_b32_e32 v3, s1
	v_lshl_add_u64 v[202:203], v[2:3], 0, s[8:9]
	v_mov_b64_e32 v[2:3], s[84:85]
	v_mad_u64_u32 v[2:3], s[0:1], v202, s40, v[2:3]
	s_lshl_b32 s82, s10, 1
	v_bfe_u32 v4, v200, 5, 1
	v_mad_i32_i24 v3, v203, s40, v3
	s_add_u32 s0, s2, s82
	v_lshl_add_u64 v[2:3], v[2:3], 0, s[82:83]
	v_lshlrev_b32_e32 v0, 4, v4
	s_addc_u32 s1, s3, 0
	v_lshl_add_u64 v[2:3], v[2:3], 0, v[0:1]
	s_add_u32 s2, s0, 0x1000
	global_load_dwordx4 v[176:179], v[2:3], off offset:2048
	global_load_dwordx4 v[180:183], v[2:3], off offset:2080
	global_load_dwordx4 v[184:187], v[2:3], off offset:2112
	global_load_dwordx4 v[188:191], v[2:3], off offset:2144
	s_addc_u32 s3, s1, 0
	s_or_b32 s9, s7, 0xc0
	v_ashrrev_i32_e32 v201, 3, v200
	v_lshlrev_b32_e32 v2, 3, v200
	v_add_u32_e32 v12, s9, v201
	v_mov_b64_e32 v[6:7], s[0:1]
	v_and_b32_e32 v2, 56, v2
	v_mad_i64_i32 v[8:9], s[10:11], v12, s40, v[6:7]
	v_lshlrev_b32_e32 v2, 1, v2
	v_mov_b32_e32 v3, v1
	v_lshl_add_u64 v[8:9], v[8:9], 0, v[2:3]
	v_mov_b64_e32 v[10:11], s[2:3]
	global_load_dwordx4 v[192:195], v[8:9], off offset:3072
	v_mad_i64_i32 v[8:9], s[10:11], v12, s40, v[10:11]
	v_lshl_add_u64 v[8:9], v[8:9], 0, v[2:3]
	global_load_dwordx4 v[196:199], v[8:9], off
	v_add_u32_e32 v8, s7, v201
	v_add_u32_e32 v12, 0x80, v8
	v_mad_i64_i32 v[6:7], s[10:11], v12, s40, v[6:7]
	v_lshl_add_u64 v[6:7], v[6:7], 0, v[2:3]
	v_mad_i64_i32 v[10:11], s[10:11], v12, s40, v[10:11]
	global_load_dwordx4 v[6:9], v[6:7], off offset:3072
	v_lshl_add_u64 v[10:11], v[10:11], 0, v[2:3]
	global_load_dwordx4 v[10:13], v[10:11], off
	s_add_i32 s25, s8, s7
	s_or_b32 s92, s25, 30
	v_lshlrev_b32_e32 v14, 4, v200
	s_cmp_le_i32 s9, s92
	v_mul_lo_u32 v3, v201, s43
	v_and_b32_e32 v14, 0x70, v14
	s_cselect_b64 s[16:17], -1, 0
	v_add3_u32 v210, 0, v3, v14
	s_mov_b64 s[8:9], -1
	s_and_b64 vcc, exec, s[16:17]
	s_waitcnt vmcnt(3)
	ds_write_b128 v210, v[192:195]
	s_waitcnt vmcnt(2)
	ds_write_b128 v210, v[196:199] offset:27648
	s_waitcnt vmcnt(1)
	ds_write_b128 v210, v[6:9] offset:9216
	s_waitcnt vmcnt(0)
	ds_write_b128 v210, v[10:13] offset:36864
	s_waitcnt lgkmcnt(0)
	s_barrier
	s_cbranch_vccnz .LBB0_331
	v_lshlrev_b32_e32 v6, 4, v4
	s_mov_b64 s[8:9], 0
